# wkv_direct: the 24 per-lane operand addresses of the 4 steps are touched before the step loop so the serialized in-loop loads hit in cache
# speedup vs baseline: 1.0050x; 1.0050x over previous
.LBB0_808:
	s_or_b64 exec, exec, s[0:1]
	v_lshlrev_b64 v[66:67], 1, v[190:191]
	v_lshl_add_u64 v[202:203], s[86:87], 0, v[66:67]
	v_lshl_add_u64 v[204:205], s[90:91], 0, v[66:67]
	v_mov_b32_e32 v70, v196
	v_ashrrev_i32_e32 v71, 31, v70
	s_movk_i32 s0, 0x1200
	v_mad_i64_i32 v[66:67], s[0:1], v70, s0, v[204:205]
	global_load_ushort v233, v[66:67], off
	global_load_ushort v233, v[66:67], off offset:1024
	global_load_ushort v233, v[66:67], off offset:2048
	v_lshlrev_b64 v[66:67], 9, v[70:71]
	v_lshl_add_u64 v[66:67], v[66:67], 0, v[190:191]
	v_lshlrev_b64 v[68:69], 1, v[66:67]
	v_lshl_add_u64 v[206:207], s[84:85], 0, v[68:69]
	global_load_ushort v233, v[206:207], off
	v_lshl_add_u64 v[206:207], v[66:67], 2, s[82:83]
	global_load_dword v233, v[206:207], off
	v_lshl_add_u64 v[206:207], s[6:7], 0, v[68:69]
	global_load_ushort v233, v[206:207], off
	v_add_u32_e32 v70, 1, v196
	v_ashrrev_i32_e32 v71, 31, v70
	s_movk_i32 s0, 0x1200
	v_mad_i64_i32 v[66:67], s[0:1], v70, s0, v[204:205]
	global_load_ushort v233, v[66:67], off
	global_load_ushort v233, v[66:67], off offset:1024
	global_load_ushort v233, v[66:67], off offset:2048
	v_lshlrev_b64 v[66:67], 9, v[70:71]
	v_lshl_add_u64 v[66:67], v[66:67], 0, v[190:191]
	v_lshlrev_b64 v[68:69], 1, v[66:67]
	v_lshl_add_u64 v[206:207], s[84:85], 0, v[68:69]
	global_load_ushort v233, v[206:207], off
	v_lshl_add_u64 v[206:207], v[66:67], 2, s[82:83]
	global_load_dword v233, v[206:207], off
	v_lshl_add_u64 v[206:207], s[6:7], 0, v[68:69]
	global_load_ushort v233, v[206:207], off
	v_add_u32_e32 v70, 2, v196
	v_ashrrev_i32_e32 v71, 31, v70
	s_movk_i32 s0, 0x1200
	v_mad_i64_i32 v[66:67], s[0:1], v70, s0, v[204:205]
	global_load_ushort v233, v[66:67], off
	global_load_ushort v233, v[66:67], off offset:1024
	global_load_ushort v233, v[66:67], off offset:2048
	v_lshlrev_b64 v[66:67], 9, v[70:71]
	v_lshl_add_u64 v[66:67], v[66:67], 0, v[190:191]
	v_lshlrev_b64 v[68:69], 1, v[66:67]
	v_lshl_add_u64 v[206:207], s[84:85], 0, v[68:69]
	global_load_ushort v233, v[206:207], off
	v_lshl_add_u64 v[206:207], v[66:67], 2, s[82:83]
	global_load_dword v233, v[206:207], off
	v_lshl_add_u64 v[206:207], s[6:7], 0, v[68:69]
	global_load_ushort v233, v[206:207], off
	v_add_u32_e32 v70, 3, v196
	v_ashrrev_i32_e32 v71, 31, v70
	s_movk_i32 s0, 0x1200
	v_mad_i64_i32 v[66:67], s[0:1], v70, s0, v[204:205]
	global_load_ushort v233, v[66:67], off
	global_load_ushort v233, v[66:67], off offset:1024
	global_load_ushort v233, v[66:67], off offset:2048
	v_lshlrev_b64 v[66:67], 9, v[70:71]
	v_lshl_add_u64 v[66:67], v[66:67], 0, v[190:191]
	v_lshlrev_b64 v[68:69], 1, v[66:67]
	v_lshl_add_u64 v[206:207], s[84:85], 0, v[68:69]
	global_load_ushort v233, v[206:207], off
	v_lshl_add_u64 v[206:207], v[66:67], 2, s[82:83]
	global_load_dword v233, v[206:207], off
	v_lshl_add_u64 v[206:207], s[6:7], 0, v[68:69]
	global_load_ushort v233, v[206:207], off
	s_mov_b64 s[8:9], 0
